# HGRN2 core stage D: 8 of the 12 state-update fragment LDS reads issued right after the last att*V MFMA (ahead of the O-store block), counted lgkmcnt waits per MFMA, redundant lgkmcnt(0) removed
# speedup vs baseline: 1.0151x; 1.0151x over previous
; #define LAS __attribute__((address_space(3)))
; template <int DK, int DVS, bool RET> ...
;     ...
;         {
;             const int tcs = (wid & 1) * 2;
;             f32x4 a0 = {0.f, 0.f, 0.f, 0.f}, a1 = {0.f, 0.f, 0.f, 0.f};
; #pragma unroll
;             for (int kk = 0; kk < DK / 32; ++kk) {
;                 const bf16x8 af = *(const LAS bf16x8*)(QD + (tr * 16 + l16) * LK + kk * 32 + quad * 8);
;                 const bf16x8 b0 = *(const LAS bf16x8*)(KD + (tcs * 16 + l16) * LK + kk * 32 + quad * 8);
;                 const bf16x8 b1 = *(const LAS bf16x8*)(KD + ((tcs + 1) * 16 + l16) * LK + kk * 32 + quad * 8);
;                 a0 = __builtin_amdgcn_mfma_f32_16x16x32_bf16(af, b0, a0, 0, 0, 0);
;                 a1 = __builtin_amdgcn_mfma_f32_16x16x32_bf16(af, b1, a1, 0, 0, 0);
;                 asm volatile("" ::: "memory");
;             }
; #pragma unroll
;             for (int j = 0; j < 4; ++j) { const int p = tr * 16 + quad * 4 + j, s0 = tcs * 16 + l16, s1 = s0 + 16;
;                 AT[p * LS + s0] = f2bf((s0 <= p) ? a0[j] : 0.f); AT[p * LS + s1] = f2bf((s1 <= p) ? a1[j] : 0.f); }
;         }
;         GLA_BAR();
; #pragma unroll
;         for (int t = 0; t < NOT; ++t) { const int tc = (wid & 1) * NOT + t; f32x4 acc = {0.f, 0.f, 0.f, 0.f};
; #pragma unroll
;             for (int kk = 0; kk < DK / 32; ++kk) {
;                 const bf16x8 af = *(const LAS bf16x8*)(QD + (tr * 16 + l16) * LK + kk * 32 + quad * 8);
;                 const bf16x8 bf = *(const LAS bf16x8*)(STB + (tc * 16 + l16) * LK + kk * 32 + quad * 8);
;                 acc = __builtin_amdgcn_mfma_f32_16x16x32_bf16(af, bf, acc, 0, 0, 0);
;                 if ((kk & 3) == 3) asm volatile("" ::: "memory"); }
;             { s16x4 v00, v01, v10, v11; const int vb = vtr + tc * 32;
;                 TRR(v00, vb, 0); TRR(v01, vb, 4 * LV * 2); TRR(v10, vb, 32 * LV * 2); TRR(v11, vb, 36 * LV * 2);
;                 const bf16x8 a0 = *(const LAS bf16x8*)(AT + (tr * 16 + l16) * LS + quad * 8), a1 = *(const LAS bf16x8*)(AT + (tr * 16 + l16) * LS + 32 + quad * 8);
;                 asm volatile("s_waitcnt lgkmcnt(0)" ::: "memory"); __builtin_amdgcn_sched_barrier(0);
;                 acc = __builtin_amdgcn_mfma_f32_16x16x32_bf16(a0, TRFRAG(v00, v01), acc, 0, 0, 0);
;                 acc = __builtin_amdgcn_mfma_f32_16x16x32_bf16(a1, TRFRAG(v10, v11), acc, 0, 0, 0); }
; #pragma unroll
.LBB0_53:
	s_waitcnt lgkmcnt(0)
	s_barrier
	ds_read_b128 v[70:73], v215
	ds_read_b128 v[234:237], v156
	ds_read_b128 v[238:241], v156 offset:4352
	ds_read_b128 v[242:245], v215 offset:64
	s_waitcnt lgkmcnt(2)
	v_mfma_f32_16x16x32_bf16 v[234:237], v[70:73], v[234:237], 0
	s_waitcnt lgkmcnt(1)
	v_mfma_f32_16x16x32_bf16 v[70:73], v[70:73], v[238:241], 0
	ds_read_b128 v[238:241], v156 offset:64
	ds_read_b128 v[246:249], v156 offset:4416
	s_waitcnt lgkmcnt(1)
	v_mfma_f32_16x16x32_bf16 v[234:237], v[242:245], v[238:241], v[234:237]
	ds_read_b128 v[238:241], v215 offset:128
	s_waitcnt lgkmcnt(1)
	v_mfma_f32_16x16x32_bf16 v[70:73], v[242:245], v[246:249], v[70:73]
	ds_read_b128 v[242:245], v156 offset:128
	ds_read_b128 v[246:249], v156 offset:4480
	s_waitcnt lgkmcnt(1)
	v_mfma_f32_16x16x32_bf16 v[234:237], v[238:241], v[242:245], v[234:237]
	ds_read_b128 v[242:245], v215 offset:192
	s_waitcnt lgkmcnt(1)
	v_mfma_f32_16x16x32_bf16 v[70:73], v[238:241], v[246:249], v[70:73]
	ds_read_b128 v[238:241], v156 offset:192
	ds_read_b128 v[246:249], v156 offset:4544
	s_waitcnt lgkmcnt(0)
	v_mfma_f32_16x16x32_bf16 v[70:73], v[242:245], v[246:249], v[70:73]
	v_mfma_f32_16x16x32_bf16 v[234:237], v[242:245], v[238:241], v[234:237]
	s_nop 6
	v_cvt_pk_bf16_f32 v70, v70, s0
	v_cndmask_b32_e64 v70, v70, 0, s[16:17]
	ds_write_b16 v206, v70 offset:32
	v_cvt_pk_bf16_f32 v70, v235, s0
	v_cndmask_b32_e64 v70, v70, 0, s[18:19]
	ds_write_b16 v207, v70
	v_cvt_pk_bf16_f32 v70, v71, s0
	v_cndmask_b32_e64 v70, v70, 0, s[20:21]
	ds_write_b16 v207, v70 offset:32
	v_cvt_pk_bf16_f32 v70, v236, s0
	v_cndmask_b32_e64 v70, v70, 0, s[22:23]
	ds_write_b16 v208, v70
	v_cvt_pk_bf16_f32 v70, v72, s0
	v_cndmask_b32_e64 v70, v70, 0, s[24:25]
	ds_write_b16 v208, v70 offset:32
	v_cvt_pk_bf16_f32 v70, v237, s0
	v_cndmask_b32_e64 v70, v70, 0, s[26:27]
	v_cvt_pk_bf16_f32 v74, v234, s0
	ds_write_b16 v209, v70
	v_cvt_pk_bf16_f32 v70, v73, s0
	v_cndmask_b32_e64 v74, v74, 0, s[14:15]
	v_cndmask_b32_e64 v70, v70, 0, s[28:29]
	ds_write_b16 v206, v74
	ds_write_b16 v209, v70 offset:32
	s_waitcnt lgkmcnt(0)
	s_barrier
	ds_read_b128 v[70:73], v215
	ds_read_b128 v[234:237], v215 offset:64
	ds_read_b128 v[238:241], v216
	ds_read_b128 v[242:245], v216 offset:64
	s_waitcnt lgkmcnt(1)
	v_mfma_f32_16x16x32_bf16 v[70:73], v[70:73], v[238:241], 0
	ds_read_b128 v[238:241], v215 offset:128
	s_waitcnt lgkmcnt(1)
	v_mfma_f32_16x16x32_bf16 v[70:73], v[234:237], v[242:245], v[70:73]
	ds_read_b128 v[234:237], v215 offset:192
	ds_read_b128 v[242:245], v216 offset:128
	ds_read_b128 v[246:249], v216 offset:192
	s_waitcnt lgkmcnt(1)
	v_mfma_f32_16x16x32_bf16 v[70:73], v[238:241], v[242:245], v[70:73]
	s_waitcnt lgkmcnt(0)
	v_mfma_f32_16x16x32_bf16 v[70:73], v[234:237], v[246:249], v[70:73]
	ds_read_b64_tr_b16 v[234:235], v157 offset:0
	ds_read_b64_tr_b16 v[236:237], v157 offset:0x140
	ds_read_b64_tr_b16 v[238:239], v157 offset:0xa00
	ds_read_b64_tr_b16 v[240:241], v157 offset:0xb40
	ds_read_b128 v[242:245], v158
	ds_read_b128 v[246:249], v158 offset:64
	s_waitcnt lgkmcnt(1)
	v_mfma_f32_16x16x32_bf16 v[70:73], v[242:245], v[234:237], v[70:73]
	v_lshl_add_u64 v[74:75], s[44:45], 0, v[62:63]
	v_lshlrev_b64 v[74:75], 11, v[74:75]
	v_lshl_add_u64 v[74:75], v[60:61], 0, v[74:75]
	s_waitcnt lgkmcnt(0)
	v_mfma_f32_16x16x32_bf16 v[70:73], v[246:249], v[238:241], v[70:73]
	ds_read_b64_tr_b16 v[234:235], v159 offset:0xa00
	ds_read_b64_tr_b16 v[236:237], v159 offset:0xb40
	ds_read_b64_tr_b16 v[238:239], v211 offset:0
	ds_read_b64_tr_b16 v[240:241], v211 offset:0x440
	ds_read_b64_tr_b16 v[242:243], v211 offset:0x2200
	ds_read_b64_tr_b16 v[244:245], v211 offset:0x2640
	ds_read_b64_tr_b16 v[246:247], v212 offset:0
	ds_read_b64_tr_b16 v[248:249], v212 offset:0x440
	s_nop 7
	v_cvt_pk_bf16_f32 v70, v70, s0
	global_store_short v[74:75], v70, off
	v_lshl_add_u64 v[74:75], s[44:45], 0, v[64:65]
	v_cvt_pk_bf16_f32 v110, v71, s0
	v_lshlrev_b64 v[70:71], 11, v[74:75]
	v_lshl_add_u64 v[70:71], v[60:61], 0, v[70:71]
	global_store_short v[70:71], v110, off
	v_lshl_add_u64 v[70:71], s[44:45], 0, v[66:67]
	v_lshlrev_b64 v[70:71], 11, v[70:71]
	v_cvt_pk_bf16_f32 v72, v72, s0
	v_lshl_add_u64 v[70:71], v[60:61], 0, v[70:71]
	global_store_short v[70:71], v72, off
	v_lshl_add_u64 v[70:71], s[44:45], 0, v[68:69]
	v_lshlrev_b64 v[70:71], 11, v[70:71]
	v_cvt_pk_bf16_f32 v72, v73, s0
	v_lshl_add_u64 v[70:71], v[60:61], 0, v[70:71]
	global_store_short v[70:71], v72, off
	ds_read_b64_tr_b16 v[70:71], v159 offset:0
	ds_read_b64_tr_b16 v[72:73], v159 offset:0x140
	ds_read_b64_tr_b16 v[110:111], v212 offset:0x2200
	ds_read_b64_tr_b16 v[112:113], v212 offset:0x2640
	s_waitcnt lgkmcnt(2)
	s_nop 0
	v_mfma_f32_16x16x32_bf16 v[0:3], v[70:73], v[238:241], v[0:3]
	ds_read_b32 v74, v218
	s_add_i32 s41, s41, -1
	s_cmpk_lg_i32 s41, 0xffbc
	v_mfma_f32_16x16x32_bf16 v[4:7], v[70:73], v[246:249], v[4:7]
	ds_read_b32 v70, v219
	s_mov_b32 s36, s40
	v_mfma_f32_16x16x32_bf16 v[0:3], v[234:237], v[242:245], v[0:3]
	s_waitcnt lgkmcnt(2)
	v_mfma_f32_16x16x32_bf16 v[4:7], v[234:237], v[110:113], v[4:7]
	s_waitcnt lgkmcnt(1)
	s_nop 5
	v_pk_mul_f32 v[2:3], v[2:3], v[74:75] op_sel_hi:[1,0]
	v_pk_mul_f32 v[0:1], v[0:1], v[74:75] op_sel_hi:[1,0]
	s_waitcnt lgkmcnt(0)
	v_pk_mul_f32 v[6:7], v[6:7], v[70:71] op_sel_hi:[1,0]
	v_pk_mul_f32 v[4:5], v[4:5], v[70:71] op_sel_hi:[1,0]
	v_mov_b32_e32 v71, v1
	v_mov_b32_e32 v72, v2
	v_mov_b32_e32 v73, v3
	v_mov_b32_e32 v74, v4
	v_mov_b32_e32 v75, v5
	v_mov_b32_e32 v234, v6
	v_mov_b32_e32 v70, v7
	s_cbranch_scc0 .LBB0_51
